# SSD: wave 4's dt cumsum moved into the LDS-latency shadow after the fragment reads (between the barriers)
# baseline (speedup 1.0000x reference)
.LBB0_352:
	v_add_u32_e32 v155, s36, v124
	v_subrev_u32_e32 v2, 48, v155
	v_cmp_lt_i32_e32 vcc, -1, v2
	v_mov_b64_e32 v[90:91], 0x1a33cc00
	v_mov_b64_e32 v[92:93], 0x1a33cc00
	s_and_saveexec_b64 s[0:1], vcc
	v_add_u32_e32 v54, s36, v125
	v_subrev_u32_e32 v54, 64, v54
	v_mad_i64_i32 v[92:93], s[20:21], v54, s29, 0
	s_or_b64 exec, exec, s[0:1]
	v_cmp_gt_u32_e64 s[0:1], -16, v2
	v_cmp_lt_i32_e32 vcc, s86, v2
	s_or_b64 s[0:1], s[64:65], s[0:1]
	s_and_b64 s[20:21], vcc, s[0:1]
	s_and_saveexec_b64 s[0:1], s[20:21]
	v_mov_b32_e32 v54, s85
	v_cmp_gt_u32_e32 vcc, -16, v2
	s_nop 1
	v_cndmask_b32_e32 v2, v231, v54, vcc
	v_add3_u32 v2, v124, v2, s36
	v_subrev_u32_e32 v2, 48, v2
	v_mad_i64_i32 v[90:91], s[20:21], v2, s29, 0
	s_or_b64 exec, exec, s[0:1]
	s_add_i32 s20, s78, -1
	s_min_u32 s0, s20, 62
	s_lshl_b32 s0, s0, 6
	s_or_b32 s21, s0, s37
	v_or_b32_e32 v54, s21, v65
	v_ashrrev_i32_e32 v55, 31, v54
	v_lshlrev_b64 v[54:55], 7, v[54:55]
	v_lshl_add_u64 v[54:55], s[62:63], 0, v[54:55]
	global_load_dword v152, v[54:55], off
	v_add_u32_e32 v158, v70, v95
	s_waitcnt vmcnt(11)
	ds_write_b128 v134, v[4:7]
	s_waitcnt vmcnt(10)
	ds_write_b128 v158, v[8:11]
	s_waitcnt vmcnt(9)
	ds_write_b128 v135, v[12:15]
	s_waitcnt vmcnt(8)
	ds_write_b128 v136, v[20:23]
	v_mov_b32_e32 v54, s87
	v_add_u32_e32 v55, v71, v96
	ds_read_b32 v54, v54
	s_waitcnt vmcnt(7)
	ds_write_b64 v55, v[58:59]
	v_add_u32_e32 v55, v71, v97
	s_waitcnt vmcnt(6)
	ds_write_b64 v55, v[60:61]
	ds_read_b64 v[88:89], v99
	ds_read_b64 v[160:161], v98
	v_lshlrev_b32_e32 v157, 16, v60
	v_lshlrev_b32_e32 v156, 16, v58
	s_mul_hi_i32 s1, s21, 0x3400
	s_waitcnt lgkmcnt(1)
	v_sub_f32_e32 v55, v54, v88
	v_mul_f32_e32 v55, 0x3fb8aa3b, v55
	v_exp_f32_e32 v88, v55
	v_sub_f32_e32 v55, v54, v89
	v_mul_f32_e32 v55, 0x3fb8aa3b, v55
	v_exp_f32_e32 v89, v55
	s_waitcnt lgkmcnt(0)
	v_pk_mul_f32 v[162:163], v[160:161], v[156:157]
	s_mulk_i32 s21, 0x3400
	v_cvt_pk_bf16_f32 v55, v162, v163
	v_pk_mul_f32 v[88:89], v[160:161], v[88:89]
	s_add_u32 s0, s96, s21
	v_pk_mul_f32 v[156:157], v[88:89], v[156:157]
	s_addc_u32 s1, s97, s1
	v_cvt_pk_bf16_f32 v153, v156, v157
	v_and_b32_e32 v157, 0xffff0000, v60
	v_and_b32_e32 v156, 0xffff0000, v58
	v_pk_mul_f32 v[162:163], v[160:161], v[156:157]
	v_pk_mul_f32 v[156:157], v[88:89], v[156:157]
	v_cvt_pk_bf16_f32 v58, v162, v163
	ds_write2_b32 v126, v55, v58 offset1:36
	v_cvt_pk_bf16_f32 v55, v156, v157
	v_lshlrev_b32_e32 v157, 16, v61
	v_lshlrev_b32_e32 v156, 16, v59
	v_and_b32_e32 v61, 0xffff0000, v61
	v_and_b32_e32 v60, 0xffff0000, v59
	v_pk_mul_f32 v[162:163], v[160:161], v[156:157]
	v_pk_mul_f32 v[58:59], v[160:161], v[60:61]
	ds_write2_b32 v137, v153, v55 offset1:36
	v_cvt_pk_bf16_f32 v55, v162, v163
	v_cvt_pk_bf16_f32 v58, v58, v59
	v_lshlrev_b32_e32 v2, 1, v62
	v_pk_mul_f32 v[156:157], v[88:89], v[156:157]
	ds_write2_b32 v126, v55, v58 offset0:72 offset1:108
	v_pk_mul_f32 v[58:59], v[88:89], v[60:61]
	v_lshlrev_b32_e32 v88, 1, v64
	v_mov_b32_e32 v89, v3
	v_lshl_add_u64 v[20:21], s[0:1], 0, v[2:3]
	v_lshl_add_u64 v[60:61], s[0:1], 0, v[88:89]
	v_lshl_add_u64 v[4:5], v[72:73], 1, v[20:21]
	v_lshl_add_u64 v[8:9], v[74:75], 1, v[20:21]
	v_lshl_add_u64 v[12:13], v[76:77], 1, v[20:21]
	v_lshl_add_u64 v[20:21], v[78:79], 1, v[20:21]
	v_cvt_pk_bf16_f32 v55, v58, v59
	v_lshl_add_u64 v[58:59], v[80:81], 1, v[60:61]
	v_lshl_add_u64 v[60:61], v[82:83], 1, v[60:61]
	global_load_dwordx4 v[4:7], v[4:5], off
	s_cmp_lg_u32 s36, 0
	global_load_dwordx4 v[8:11], v[8:9], off
	v_cvt_pk_bf16_f32 v153, v156, v157
	global_load_dwordx4 v[12:15], v[12:13], off
	s_cselect_b64 s[0:1], -1, 0
	global_load_dwordx4 v[20:23], v[20:21], off
	s_max_u32 s21, s20, 1
	global_load_dwordx2 v[58:59], v[58:59], off
	ds_write2_b32 v137, v153, v55 offset0:72 offset1:108
	global_load_dwordx2 v[60:61], v[60:61], off
	v_lshl_add_u32 v55, s21, 6, v103
	v_cmp_lt_i32_e32 vcc, -1, v55
	s_waitcnt lgkmcnt(0)
	s_barrier
	s_cmp_eq_u64 s[82:83], 0
	s_cbranch_scc1 .Lssq1_own
	v_lshlrev_b32_e32 v201, 2, v232
	global_store_dword v201, v3, s[66:67]
	s_branch .LBB0_360

.LBB0_360:
	v_add_u32_e32 v156, v106, v107
	ds_read_b128 v[160:163], v156 offset:34816
	ds_read_b128 v[164:167], v156 offset:34880
	ds_read_b128 v[168:171], v156 offset:17408
	ds_read_b128 v[172:175], v156 offset:17472
	ds_read_b128 v[176:179], v138
	ds_read_b128 v[180:183], v138 offset:64
	ds_read_b128 v[184:187], v138 offset:4352
	ds_read_b128 v[188:191], v138 offset:4416
	ds_read_b128 v[192:195], v156 offset:34944
	ds_read_b128 v[202:205], v156 offset:35008
	ds_read_b128 v[206:209], v156 offset:17536
	ds_read_b128 v[210:213], v156 offset:17600
	ds_read_b128 v[214:217], v138 offset:128
	ds_read_b128 v[236:239], v138 offset:192
	ds_read_b128 v[240:243], v138 offset:4480
	ds_read_b128 v[244:247], v138 offset:4544
	s_cmp_eq_u32 s98, 0
	s_cbranch_scc1 .Lscan1_skip
	s_cmp_eq_u32 s81, 64
	s_cbranch_scc1 .Lscan1_skip
	v_mul_f32_e64 v198, v57, -v63
	v_mov_b32_e32 v199, v3
	s_nop 1
	v_mov_b32_dpp v199, v198 row_shr:1 row_mask:0xf bank_mask:0xf
	v_fma_f32 v198, v57, -v63, v199
	v_mov_b32_e32 v199, v3
	s_nop 0
	v_add_f32_dpp v198, v198, v198 row_shr:2 row_mask:0xf bank_mask:0xf bound_ctrl:1
	s_nop 1
	v_add_f32_dpp v198, v198, v198 row_shr:4 row_mask:0xf bank_mask:0xf bound_ctrl:1
	s_nop 1
	v_add_f32_dpp v198, v198, v198 row_shr:8 row_mask:0xf bank_mask:0xf bound_ctrl:1
	s_nop 1
	v_mov_b32_dpp v199, v198 row_bcast:15 row_mask:0xa bank_mask:0xf
	v_add_f32_e32 v198, v198, v199
	v_mov_b32_e32 v199, v3
	s_nop 1
	v_mov_b32_dpp v199, v198 row_bcast:31 row_mask:0xc bank_mask:0xf
	v_add_f32_e32 v198, v198, v199
.Lscan1_skip:
	s_waitcnt lgkmcnt(11)
	v_mfma_f32_16x16x32_bf16 v[248:251], v[160:163], v[176:179], 0
	v_mfma_f32_16x16x32_bf16 v[176:179], v[168:171], v[176:179], 0
	s_waitcnt lgkmcnt(9)
	v_mfma_f32_16x16x32_bf16 v[160:163], v[160:163], v[184:187], 0
	v_mfma_f32_16x16x32_bf16 v[168:171], v[168:171], v[184:187], 0
	v_mfma_f32_16x16x32_bf16 v[184:187], v[164:167], v[180:183], v[248:251]
	v_mfma_f32_16x16x32_bf16 v[176:179], v[172:175], v[180:183], v[176:179]
	s_waitcnt lgkmcnt(8)
	v_mfma_f32_16x16x32_bf16 v[160:163], v[164:167], v[188:191], v[160:163]
	v_mfma_f32_16x16x32_bf16 v[164:167], v[172:175], v[188:191], v[168:171]
	s_waitcnt lgkmcnt(3)
	v_mfma_f32_16x16x32_bf16 v[168:171], v[192:195], v[214:217], v[184:187]
	v_mfma_f32_16x16x32_bf16 v[172:175], v[206:209], v[214:217], v[176:179]
	s_waitcnt lgkmcnt(1)
	v_mfma_f32_16x16x32_bf16 v[160:163], v[192:195], v[240:243], v[160:163]
	s_nop 0
	ds_read_b128 v[176:179], v139
	ds_read_b64_tr_b16 v[180:181], v140
	ds_read_b64_tr_b16 v[182:183], v140 offset:1088
	ds_read_b64_tr_b16 v[184:185], v140 offset:32
	ds_read_b64_tr_b16 v[186:187], v140 offset:1120
	ds_read_b64_tr_b16 v[188:189], v140 offset:64
	ds_read_b64_tr_b16 v[190:191], v140 offset:1152
	ds_read_b64_tr_b16 v[192:193], v140 offset:96
	ds_read_b64_tr_b16 v[194:195], v140 offset:1184
	v_mfma_f32_16x16x32_bf16 v[164:167], v[206:209], v[240:243], v[164:167]
	s_waitcnt lgkmcnt(9)
	v_mfma_f32_16x16x32_bf16 v[160:163], v[202:205], v[244:247], v[160:163]
	v_mfma_f32_16x16x32_bf16 v[168:171], v[202:205], v[236:239], v[168:171]
	v_mfma_f32_16x16x32_bf16 v[172:175], v[210:213], v[236:239], v[172:175]
	v_mfma_f32_16x16x32_bf16 v[164:167], v[210:213], v[244:247], v[164:167]
	s_cmp_eq_u32 s98, 0
	s_cbranch_scc1 .Lscan1w_skip
	s_cmp_eq_u32 s81, 64
	s_cbranch_scc1 .Lscan1w_skip
	ds_write_b32 v104, v57
	ds_write_b32 v105, v198
.Lscan1w_skip:
	ds_read_b32 v55, v109
	ds_read_b128 v[202:205], v127
	s_waitcnt lgkmcnt(0)
	v_pk_add_f32 v[198:199], v[54:55], v[202:203] op_sel:[1,0] op_sel_hi:[1,1] neg_lo:[0,1] neg_hi:[0,1]
	v_pk_add_f32 v[222:223], v[54:55], v[204:205] op_sel:[1,0] op_sel_hi:[1,1] neg_lo:[0,1] neg_hi:[0,1]
	v_pk_mul_f32 v[198:199], v[198:199], s[100:101]
	v_pk_mul_f32 v[222:223], v[222:223], s[100:101]
	v_exp_f32_e32 v198, v198
	v_exp_f32_e32 v199, v199
	v_exp_f32_e32 v222, v222
	v_exp_f32_e32 v223, v223
	v_pk_mul_f32 v[198:199], v[172:173], v[198:199]
	v_pk_mul_f32 v[222:223], v[174:175], v[222:223]
	v_cndmask_b32_e64 v198, v198, 0, s[42:43]
	v_cndmask_b32_e64 v199, 0, v199, s[44:45]
	v_cndmask_b32_e64 v222, v222, 0, s[46:47]
	v_cndmask_b32_e64 v223, v223, 0, s[48:49]
	v_cvt_pk_bf16_f32 v172, v198, v199
	v_cvt_pk_bf16_f32 v173, v222, v223
	ds_write_b64 v144, v[172:173]
	ds_read_b32 v89, v110
	ds_read_b128 v[172:175], v127
	v_mul_f32_e32 v55, 0x3fb8aa3b, v55
	v_exp_f32_e32 v154, v55
	s_waitcnt lgkmcnt(0)
	v_mul_f32_e32 v55, 0x3fb8aa3b, v89
	v_pk_add_f32 v[198:199], v[88:89], v[172:173] op_sel:[1,0] op_sel_hi:[1,1] neg_lo:[0,1] neg_hi:[0,1]
	v_pk_add_f32 v[222:223], v[88:89], v[174:175] op_sel:[1,0] op_sel_hi:[1,1] neg_lo:[0,1] neg_hi:[0,1]
	v_pk_mul_f32 v[198:199], v[198:199], s[100:101]
	v_pk_mul_f32 v[222:223], v[222:223], s[100:101]
	v_exp_f32_e32 v198, v198
	v_exp_f32_e32 v199, v199
	v_exp_f32_e32 v222, v222
	v_exp_f32_e32 v223, v223
	v_exp_f32_e32 v206, v55
	v_pk_mul_f32 v[198:199], v[164:165], v[198:199]
	v_pk_mul_f32 v[222:223], v[166:167], v[222:223]
	v_cndmask_b32_e64 v198, v198, 0, s[50:51]
	v_cndmask_b32_e64 v199, 0, v199, s[52:53]
	v_cndmask_b32_e64 v222, v222, 0, s[54:55]
	v_cndmask_b32_e64 v223, v223, 0, s[56:57]
	v_cvt_pk_bf16_f32 v164, v198, v199
	v_cvt_pk_bf16_f32 v165, v222, v223
	ds_write_b64 v145, v[164:165]
	v_mul_f32_e32 v54, 0x3fb8aa3b, v54
	v_exp_f32_e32 v54, v54
	ds_read_b64_tr_b16 v[164:165], v140 offset:8704
	ds_read_b64_tr_b16 v[166:167], v140 offset:9792
	v_add_u32_e32 v159, v108, v111
	ds_read_b128 v[172:175], v159
	v_pk_mul_f32 v[50:51], v[50:51], v[54:55] op_sel_hi:[1,0]
	v_pk_mul_f32 v[48:49], v[48:49], v[54:55] op_sel_hi:[1,0]
	v_pk_mul_f32 v[42:43], v[42:43], v[54:55] op_sel_hi:[1,0]
	v_pk_mul_f32 v[40:41], v[40:41], v[54:55] op_sel_hi:[1,0]
	v_pk_mul_f32 v[46:47], v[46:47], v[54:55] op_sel_hi:[1,0]
	v_pk_mul_f32 v[44:45], v[44:45], v[54:55] op_sel_hi:[1,0]
	v_pk_mul_f32 v[38:39], v[38:39], v[54:55] op_sel_hi:[1,0]
	v_pk_mul_f32 v[36:37], v[36:37], v[54:55] op_sel_hi:[1,0]
	v_mfma_f32_16x16x32_bf16 v[48:51], v[180:183], v[176:179], v[48:51]
	v_add_u32_e32 v54, v112, v113
	v_mfma_f32_16x16x32_bf16 v[40:43], v[184:187], v[176:179], v[40:43]
	v_mfma_f32_16x16x32_bf16 v[44:47], v[188:191], v[176:179], v[44:47]
	v_mfma_f32_16x16x32_bf16 v[36:39], v[192:195], v[176:179], v[36:39]
	ds_read_b64_tr_b16 v[176:177], v140 offset:8736
	ds_read_b64_tr_b16 v[178:179], v140 offset:9824
	s_waitcnt lgkmcnt(2)
	v_mfma_f32_16x16x32_bf16 v[48:51], v[164:167], v[172:175], v[48:51]
	ds_read_b64_tr_b16 v[164:165], v140 offset:8768
	ds_read_b64_tr_b16 v[166:167], v140 offset:9856
	ds_read_b64_tr_b16 v[180:181], v140 offset:8800
	ds_read_b64_tr_b16 v[182:183], v140 offset:9888
	s_waitcnt lgkmcnt(0)
	s_barrier
	s_waitcnt lgkmcnt(2)
	v_mfma_f32_16x16x32_bf16 v[40:43], v[176:179], v[172:175], v[40:43]
	ds_read_b128 v[176:179], v54
	ds_read_b128 v[184:187], v150
	v_add_u32_e32 v54, v112, v111
	s_waitcnt lgkmcnt(3)
	v_mfma_f32_16x16x32_bf16 v[44:47], v[164:167], v[172:175], v[44:47]
	ds_read_b128 v[164:167], v150 offset:2304
	ds_read_b128 v[188:191], v150 offset:64
	ds_read_b128 v[192:195], v54
	ds_read_b128 v[202:205], v150 offset:2368
	s_waitcnt lgkmcnt(6)
	v_mfma_f32_16x16x32_bf16 v[36:39], v[180:183], v[172:175], v[36:39]
	v_mul_f32_e64 v170, v170, v154
	v_mul_f32_e64 v171, v171, v154
	v_pk_mul_f32 v[168:169], v[168:169], v[154:155] op_sel_hi:[1,0]
	v_pk_mul_f32 v[162:163], v[162:163], v[206:207] op_sel_hi:[1,0]
	v_pk_mul_f32 v[160:161], v[160:161], v[206:207] op_sel_hi:[1,0]
	s_waitcnt lgkmcnt(4)
	v_mfma_f32_16x16x32_bf16 v[168:171], v[176:179], v[184:187], v[168:171]
	v_cvt_pk_bf16_f32 v54, v48, v49
	v_cvt_pk_bf16_f32 v55, v50, v51
	v_cvt_pk_bf16_f32 v172, v40, v41
	v_cvt_pk_bf16_f32 v173, v42, v43
	v_add_u32_e32 v157, 0x8800, v151
	s_waitcnt lgkmcnt(3)
	v_mfma_f32_16x16x32_bf16 v[160:163], v[176:179], v[164:167], v[160:163]
	ds_write2_b64 v157, v[54:55], v[172:173] offset1:4
	v_cvt_pk_bf16_f32 v54, v44, v45
	v_cvt_pk_bf16_f32 v55, v46, v47
	s_waitcnt lgkmcnt(2)
	v_mfma_f32_16x16x32_bf16 v[164:167], v[192:195], v[188:191], v[168:171]
	v_cmp_lt_i32_e32 vcc, v225, v220
	v_lshl_add_u64 v[92:93], v[86:87], 0, v[92:93]
	s_nop 0
	v_cvt_pk_bf16_f32 v168, v36, v37
	v_cvt_pk_bf16_f32 v169, v38, v39
	ds_write2_b64 v157, v[54:55], v[168:169] offset0:8 offset1:12
	v_cndmask_b32_e32 v54, v218, v225, vcc
	v_lshlrev_b32_e32 v153, 2, v54
	s_waitcnt vmcnt(9)
	v_lshlrev_b32_e32 v54, 16, v52
	v_and_b32_e32 v55, 0xffff0000, v52
	v_mul_f32_e32 v52, 0xbfb8aa3b, v54
	v_exp_f32_e32 v52, v52
	v_mul_f32_e32 v89, 0xbfb8aa3b, v55
	v_exp_f32_e32 v89, v89
	ds_read_b64 v[168:169], v128
	v_add_f32_e32 v52, 1.0, v52
	v_rcp_f32_e32 v170, v52
	v_add_f32_e32 v52, 1.0, v89
	v_rcp_f32_e32 v171, v52
	s_waitcnt lgkmcnt(0)
	v_lshlrev_b32_e32 v172, 16, v168
	v_and_b32_e32 v173, 0xffff0000, v168
	v_pk_fma_f32 v[164:165], v[0:1], v[172:173], v[164:165]
	v_pk_mul_f32 v[54:55], v[170:171], v[54:55]
	v_lshlrev_b32_e32 v52, 16, v53
	v_pk_mul_f32 v[164:165], v[54:55], v[164:165]
	v_and_b32_e32 v53, 0xffff0000, v53
	v_mul_f32_e32 v54, 0xbfb8aa3b, v52
	v_exp_f32_e32 v89, v54
	v_mul_f32_e32 v54, 0xbfb8aa3b, v53
	v_exp_f32_e32 v154, v54
	v_lshlrev_b32_e32 v168, 16, v169
	v_add_f32_e32 v89, 1.0, v89
	v_rcp_f32_e32 v170, v89
	v_add_f32_e32 v89, 1.0, v154
	v_rcp_f32_e32 v171, v89
	v_and_b32_e32 v169, 0xffff0000, v169
	v_pk_fma_f32 v[166:167], v[0:1], v[168:169], v[166:167]
	v_pk_mul_f32 v[54:55], v[164:165], v[164:165]
	v_pk_mul_f32 v[52:53], v[170:171], v[52:53]
	v_add_f32_e32 v54, v54, v55
	v_pk_mul_f32 v[166:167], v[52:53], v[166:167]
	v_cmp_lt_i32_e32 vcc, v226, v220
	v_pk_mul_f32 v[52:53], v[166:167], v[166:167]
	s_nop 0
	v_add_f32_e32 v52, v52, v54
	v_add_f32_e32 v89, v53, v52
	ds_bpermute_b32 v168, v153, v89
	v_cndmask_b32_e32 v154, v218, v226, vcc
	v_lshlrev_b32_e32 v154, 2, v154
	v_mfma_f32_16x16x32_bf16 v[52:55], v[192:195], v[202:205], v[160:163]
	s_waitcnt lgkmcnt(0)
	v_add_f32_e32 v89, v89, v168
	s_nop 0
	ds_bpermute_b32 v160, v154, v89
	v_cvt_pk_bf16_f32 v162, v164, v165
	v_cvt_pk_bf16_f32 v163, v166, v167
	global_store_dwordx2 v[92:93], v[162:163], off
	s_and_saveexec_b64 s[0:1], s[58:59]
	s_cbranch_execz .LBB0_362
	s_waitcnt lgkmcnt(0)
	v_add_f32_e32 v89, v89, v160
	ds_write_b32 v114, v89

.LBB0_364:
	s_or_b64 exec, exec, s[0:1]
	s_min_u32 s0, s20, 63
	v_lshl_or_b32 v54, s0, 6, v94
	v_add_u32_e32 v52, s74, v54
	s_waitcnt lgkmcnt(0)
	v_mad_i64_i32 v[52:53], s[0:1], v52, s29, v[86:87]
	v_add_u32_e32 v54, s75, v54
	v_mad_i64_i32 v[54:55], s[0:1], v54, s29, v[86:87]
	global_load_dwordx2 v[52:53], v[52:53], off
	s_nop 0
	global_load_dwordx2 v[84:85], v[54:55], off
	s_or_b32 s0, s81, 1
	s_cmp_gt_u32 s0, 64
	s_cbranch_scc1 .LBB0_351
	v_add_u32_e32 v54, 16, v155
	v_cmp_lt_i32_e32 vcc, -1, v54
	v_mov_b64_e32 v[90:91], 0x1a33cc00
	v_mov_b64_e32 v[92:93], 0x1a33cc00
	s_and_saveexec_b64 s[0:1], vcc
	v_add_u32_e32 v55, s36, v125
	v_mad_i64_i32 v[92:93], s[20:21], v55, s29, 0
	s_or_b64 exec, exec, s[0:1]
	v_cmp_gt_u32_e64 s[0:1], -16, v54
	v_cmp_lt_i32_e32 vcc, s86, v54
	s_or_b64 s[0:1], s[64:65], s[0:1]
	s_and_b64 s[20:21], vcc, s[0:1]
	s_and_saveexec_b64 s[0:1], s[20:21]
	v_mov_b32_e32 v55, s85
	v_cmp_gt_u32_e32 vcc, -16, v54
	s_nop 1
	v_cndmask_b32_e32 v54, v231, v55, vcc
	v_add_u32_e32 v54, v124, v54
	v_add3_u32 v54, v54, s36, 16
	v_mad_i64_i32 v[90:91], s[20:21], v54, s29, 0
	s_or_b64 exec, exec, s[0:1]
	s_min_u32 s0, s78, 62
	s_lshl_b32 s20, s0, 6
	s_add_i32 s20, s20, s37
	v_or_b32_e32 v54, s20, v65
	v_ashrrev_i32_e32 v55, 31, v54
	v_lshlrev_b64 v[54:55], 7, v[54:55]
	v_lshl_add_u64 v[54:55], s[62:63], 0, v[54:55]
	global_load_dword v57, v[54:55], off
	ds_write_b128 v134, v[16:19]
	ds_write_b128 v158, v[24:27]
	ds_write_b128 v135, v[28:31]
	ds_write_b128 v136, v[32:35]
	s_mul_hi_i32 s1, s20, 0x3400
	s_mulk_i32 s20, 0x3400
	s_add_u32 s0, s96, s20
	s_addc_u32 s1, s97, s1
	v_readlane_b32 s2, v254, 36
	v_lshl_add_u64 v[32:33], s[0:1], 0, v[2:3]
	v_add_u32_e32 v54, v115, v96
	v_mov_b32_e32 v2, s2
	ds_read_b32 v2, v2
	ds_write_b64 v54, v[66:67]
	v_add_u32_e32 v54, v115, v97
	ds_write_b64 v54, v[68:69]
	ds_read_b64 v[54:55], v117
	ds_read_b64 v[162:163], v116
	v_lshlrev_b32_e32 v161, 16, v68
	v_lshlrev_b32_e32 v160, 16, v66
	v_lshl_add_u64 v[16:17], v[72:73], 1, v[32:33]
	s_waitcnt lgkmcnt(1)
	v_sub_f32_e32 v54, v2, v54
	v_sub_f32_e32 v55, v2, v55
	v_mul_f32_e32 v54, 0x3fb8aa3b, v54
	v_mul_f32_e32 v55, 0x3fb8aa3b, v55
	v_exp_f32_e32 v54, v54
	v_exp_f32_e32 v55, v55
	s_waitcnt lgkmcnt(0)
	v_pk_mul_f32 v[164:165], v[162:163], v[160:161]
	v_lshl_add_u64 v[24:25], v[74:75], 1, v[32:33]
	v_cvt_pk_bf16_f32 v89, v164, v165
	v_pk_mul_f32 v[54:55], v[162:163], v[54:55]
	v_lshl_add_u64 v[28:29], v[76:77], 1, v[32:33]
	v_pk_mul_f32 v[160:161], v[54:55], v[160:161]
	v_lshl_add_u64 v[32:33], v[78:79], 1, v[32:33]
	v_cvt_pk_bf16_f32 v155, v160, v161
	v_and_b32_e32 v161, 0xffff0000, v68
	v_and_b32_e32 v160, 0xffff0000, v66
	v_pk_mul_f32 v[164:165], v[162:163], v[160:161]
	v_pk_mul_f32 v[160:161], v[54:55], v[160:161]
	v_cvt_pk_bf16_f32 v66, v164, v165
	ds_write2_b32 v130, v89, v66 offset1:36
	v_cvt_pk_bf16_f32 v66, v160, v161
	v_lshlrev_b32_e32 v161, 16, v69
	v_lshlrev_b32_e32 v160, 16, v67
	v_and_b32_e32 v69, 0xffff0000, v69
	v_and_b32_e32 v68, 0xffff0000, v67
	ds_write2_b32 v137, v155, v66 offset1:36
	v_pk_mul_f32 v[164:165], v[162:163], v[160:161]
	v_pk_mul_f32 v[66:67], v[162:163], v[68:69]
	v_cvt_pk_bf16_f32 v89, v164, v165
	v_pk_mul_f32 v[160:161], v[54:55], v[160:161]
	v_cvt_pk_bf16_f32 v66, v66, v67
	v_pk_mul_f32 v[54:55], v[54:55], v[68:69]
	v_cvt_pk_bf16_f32 v155, v160, v161
	ds_write2_b32 v130, v89, v66 offset0:72 offset1:108
	v_cvt_pk_bf16_f32 v54, v54, v55
	v_mov_b32_e32 v89, v3
	ds_write2_b32 v137, v155, v54 offset0:72 offset1:108
	v_lshl_add_u64 v[54:55], s[0:1], 0, v[88:89]
	v_lshl_add_u64 v[66:67], v[80:81], 1, v[54:55]
	v_lshl_add_u64 v[54:55], v[82:83], 1, v[54:55]
	global_load_dwordx4 v[16:19], v[16:17], off
	v_add_u32_e32 v155, s36, v123
	global_load_dwordx4 v[24:27], v[24:25], off
	v_cmp_lt_i32_e32 vcc, -1, v155
	global_load_dwordx4 v[28:31], v[28:29], off
	s_and_b64 s[0:1], s[40:41], vcc
	global_load_dwordx4 v[32:35], v[32:33], off
	v_cmp_lt_u32_e32 vcc, 15, v155
	global_load_dwordx2 v[66:67], v[66:67], off
	s_or_b64 s[20:21], s[64:65], vcc
	global_load_dwordx2 v[68:69], v[54:55], off
	s_waitcnt lgkmcnt(0)
	s_barrier
	s_cmp_eq_u64 s[82:83], 0
	s_cbranch_scc1 .Lssq2_own
	v_lshlrev_b32_e32 v201, 2, v232
	global_store_dword v201, v3, s[66:67]
	s_branch .LBB0_373

.LBB0_373:
	ds_read_b128 v[160:163], v156 offset:34816
	ds_read_b128 v[164:167], v156 offset:34880
	ds_read_b128 v[168:171], v156 offset:17408
	ds_read_b128 v[172:175], v156 offset:17472
	ds_read_b128 v[176:179], v138
	ds_read_b128 v[180:183], v138 offset:64
	ds_read_b128 v[184:187], v138 offset:4352
	ds_read_b128 v[188:191], v138 offset:4416
	ds_read_b128 v[192:195], v156 offset:34944
	ds_read_b128 v[202:205], v156 offset:35008
	ds_read_b128 v[206:209], v156 offset:17536
	ds_read_b128 v[210:213], v156 offset:17600
	ds_read_b128 v[214:217], v138 offset:128
	ds_read_b128 v[236:239], v138 offset:192
	ds_read_b128 v[240:243], v138 offset:4480
	ds_read_b128 v[244:247], v138 offset:4544
	s_cmp_eq_u32 s98, 0
	s_cbranch_scc1 .Lscan2_skip
	s_waitcnt vmcnt(19)
	v_mul_f32_e64 v198, v152, -v63
	v_mov_b32_e32 v199, v3
	s_nop 1
	v_mov_b32_dpp v199, v198 row_shr:1 row_mask:0xf bank_mask:0xf
	v_fma_f32 v198, v152, -v63, v199
	v_mov_b32_e32 v199, v3
	s_nop 0
	v_add_f32_dpp v198, v198, v198 row_shr:2 row_mask:0xf bank_mask:0xf bound_ctrl:1
	s_nop 1
	v_add_f32_dpp v198, v198, v198 row_shr:4 row_mask:0xf bank_mask:0xf bound_ctrl:1
	s_nop 1
	v_add_f32_dpp v198, v198, v198 row_shr:8 row_mask:0xf bank_mask:0xf bound_ctrl:1
	s_nop 1
	v_mov_b32_dpp v199, v198 row_bcast:15 row_mask:0xa bank_mask:0xf
	v_add_f32_e32 v198, v198, v199
	v_mov_b32_e32 v199, v3
	s_nop 1
	v_mov_b32_dpp v199, v198 row_bcast:31 row_mask:0xc bank_mask:0xf
	v_add_f32_e32 v198, v198, v199
.Lscan2_skip:
	s_waitcnt lgkmcnt(11)
	v_mfma_f32_16x16x32_bf16 v[248:251], v[160:163], v[176:179], 0
	v_mfma_f32_16x16x32_bf16 v[176:179], v[168:171], v[176:179], 0
	s_waitcnt lgkmcnt(9)
	v_mfma_f32_16x16x32_bf16 v[160:163], v[160:163], v[184:187], 0
	v_mfma_f32_16x16x32_bf16 v[168:171], v[168:171], v[184:187], 0
	v_mfma_f32_16x16x32_bf16 v[184:187], v[164:167], v[180:183], v[248:251]
	v_mfma_f32_16x16x32_bf16 v[176:179], v[172:175], v[180:183], v[176:179]
	s_waitcnt lgkmcnt(8)
	v_mfma_f32_16x16x32_bf16 v[160:163], v[164:167], v[188:191], v[160:163]
	v_mfma_f32_16x16x32_bf16 v[164:167], v[172:175], v[188:191], v[168:171]
	s_waitcnt lgkmcnt(3)
	v_mfma_f32_16x16x32_bf16 v[168:171], v[192:195], v[214:217], v[184:187]
	v_mfma_f32_16x16x32_bf16 v[172:175], v[206:209], v[214:217], v[176:179]
	s_waitcnt lgkmcnt(1)
	v_mfma_f32_16x16x32_bf16 v[160:163], v[192:195], v[240:243], v[160:163]
	s_nop 0
	ds_read_b128 v[176:179], v139
	ds_read_b64_tr_b16 v[180:181], v140
	ds_read_b64_tr_b16 v[182:183], v140 offset:1088
	ds_read_b64_tr_b16 v[184:185], v140 offset:32
	ds_read_b64_tr_b16 v[186:187], v140 offset:1120
	ds_read_b64_tr_b16 v[188:189], v140 offset:64
	ds_read_b64_tr_b16 v[190:191], v140 offset:1152
	ds_read_b64_tr_b16 v[192:193], v140 offset:96
	ds_read_b64_tr_b16 v[194:195], v140 offset:1184
	v_mfma_f32_16x16x32_bf16 v[164:167], v[206:209], v[240:243], v[164:167]
	v_mfma_f32_16x16x32_bf16 v[168:171], v[202:205], v[236:239], v[168:171]
	v_mfma_f32_16x16x32_bf16 v[172:175], v[210:213], v[236:239], v[172:175]
	s_waitcnt lgkmcnt(9)
	v_mfma_f32_16x16x32_bf16 v[160:163], v[202:205], v[244:247], v[160:163]
	v_mfma_f32_16x16x32_bf16 v[164:167], v[210:213], v[244:247], v[164:167]
	s_cmp_eq_u32 s98, 0
	s_cbranch_scc1 .Lscan2w_skip
	ds_write_b32 v118, v152
	ds_write_b32 v119, v198
.Lscan2w_skip:
	ds_read_b32 v88, v120
	ds_read_b128 v[202:205], v131
	s_waitcnt lgkmcnt(0)
	v_pk_add_f32 v[198:199], v[88:89], v[202:203] op_sel:[0,0] op_sel_hi:[0,1] neg_lo:[0,1] neg_hi:[0,1]
	v_pk_add_f32 v[222:223], v[88:89], v[204:205] op_sel:[0,0] op_sel_hi:[0,1] neg_lo:[0,1] neg_hi:[0,1]
	v_pk_mul_f32 v[198:199], v[198:199], s[100:101]
	v_pk_mul_f32 v[222:223], v[222:223], s[100:101]
	v_exp_f32_e32 v198, v198
	v_exp_f32_e32 v199, v199
	v_exp_f32_e32 v222, v222
	v_exp_f32_e32 v223, v223
	v_pk_mul_f32 v[198:199], v[172:173], v[198:199]
	v_pk_mul_f32 v[222:223], v[174:175], v[222:223]
	v_cndmask_b32_e64 v198, v198, 0, s[42:43]
	v_cndmask_b32_e64 v199, 0, v199, s[44:45]
	v_cndmask_b32_e64 v222, v222, 0, s[46:47]
	v_cndmask_b32_e64 v223, v223, 0, s[48:49]
	v_cvt_pk_bf16_f32 v54, v198, v199
	v_cvt_pk_bf16_f32 v55, v222, v223
	ds_write_b64 v144, v[54:55]
	ds_read_b32 v55, v121
	ds_read_b128 v[172:175], v131
	v_mul_f32_e32 v54, 0x3fb8aa3b, v88
	v_exp_f32_e32 v54, v54
	s_waitcnt lgkmcnt(0)
	v_mul_f32_e32 v88, 0x3fb8aa3b, v55
	v_pk_add_f32 v[198:199], v[54:55], v[172:173] op_sel:[1,0] op_sel_hi:[1,1] neg_lo:[0,1] neg_hi:[0,1]
	v_pk_add_f32 v[222:223], v[54:55], v[174:175] op_sel:[1,0] op_sel_hi:[1,1] neg_lo:[0,1] neg_hi:[0,1]
	v_pk_mul_f32 v[198:199], v[198:199], s[100:101]
	v_pk_mul_f32 v[222:223], v[222:223], s[100:101]
	v_exp_f32_e32 v198, v198
	v_exp_f32_e32 v199, v199
	v_exp_f32_e32 v222, v222
	v_exp_f32_e32 v223, v223
	v_exp_f32_e32 v88, v88
	v_pk_mul_f32 v[198:199], v[164:165], v[198:199]
	v_pk_mul_f32 v[222:223], v[166:167], v[222:223]
	v_cndmask_b32_e64 v198, v198, 0, s[50:51]
	v_cndmask_b32_e64 v199, 0, v199, s[52:53]
	v_cndmask_b32_e64 v222, v222, 0, s[54:55]
	v_cndmask_b32_e64 v223, v223, 0, s[56:57]
	v_cvt_pk_bf16_f32 v164, v198, v199
	v_cvt_pk_bf16_f32 v165, v222, v223
	ds_write_b64 v145, v[164:165]
	v_mul_f32_e32 v2, 0x3fb8aa3b, v2
	v_exp_f32_e32 v2, v2
	ds_read_b128 v[164:167], v159
	ds_read_b64_tr_b16 v[172:173], v140 offset:8704
	ds_read_b64_tr_b16 v[174:175], v140 offset:9792
	v_add_u32_e32 v55, v122, v111
	v_pk_mul_f32 v[50:51], v[50:51], v[2:3] op_sel_hi:[1,0]
	v_pk_mul_f32 v[48:49], v[48:49], v[2:3] op_sel_hi:[1,0]
	v_pk_mul_f32 v[42:43], v[42:43], v[2:3] op_sel_hi:[1,0]
	v_pk_mul_f32 v[40:41], v[40:41], v[2:3] op_sel_hi:[1,0]
	v_mfma_f32_16x16x32_bf16 v[48:51], v[180:183], v[176:179], v[48:51]
	v_mul_f32_e64 v46, v46, v2
	v_mul_f32_e64 v47, v47, v2
	v_pk_mul_f32 v[44:45], v[44:45], v[2:3] op_sel_hi:[1,0]
	v_pk_mul_f32 v[38:39], v[38:39], v[2:3] op_sel_hi:[1,0]
	v_pk_mul_f32 v[36:37], v[36:37], v[2:3] op_sel_hi:[1,0]
	v_mfma_f32_16x16x32_bf16 v[40:43], v[184:187], v[176:179], v[40:43]
	v_add_u32_e32 v2, v122, v113
	v_mfma_f32_16x16x32_bf16 v[44:47], v[188:191], v[176:179], v[44:47]
	v_mfma_f32_16x16x32_bf16 v[36:39], v[192:195], v[176:179], v[36:39]
	ds_read_b64_tr_b16 v[176:177], v140 offset:8736
	ds_read_b64_tr_b16 v[178:179], v140 offset:9824
	ds_read_b64_tr_b16 v[180:181], v140 offset:8768
	ds_read_b64_tr_b16 v[182:183], v140 offset:9856
	s_waitcnt lgkmcnt(4)
	v_mfma_f32_16x16x32_bf16 v[48:51], v[172:175], v[164:167], v[48:51]
	ds_read_b64_tr_b16 v[172:173], v140 offset:8800
	ds_read_b64_tr_b16 v[174:175], v140 offset:9888
	s_waitcnt lgkmcnt(0)
	s_barrier
	s_waitcnt lgkmcnt(2)
	v_mfma_f32_16x16x32_bf16 v[40:43], v[176:179], v[164:167], v[40:43]
	ds_read_b128 v[176:179], v2
	ds_read_b128 v[184:187], v55
	s_waitcnt lgkmcnt(3)
	v_mfma_f32_16x16x32_bf16 v[44:47], v[180:183], v[164:167], v[44:47]
	ds_read_b128 v[180:183], v150
	ds_read_b128 v[188:191], v150 offset:64
	ds_read_b128 v[192:195], v150 offset:2304
	ds_read_b128 v[202:205], v150 offset:2368
	s_waitcnt lgkmcnt(6)
	v_mfma_f32_16x16x32_bf16 v[36:39], v[172:175], v[164:167], v[36:39]
	v_mul_f32_e64 v166, v170, v54
	v_mul_f32_e64 v167, v171, v54
	v_pk_mul_f32 v[164:165], v[168:169], v[54:55] op_sel_hi:[1,0]
	v_pk_mul_f32 v[162:163], v[162:163], v[88:89] op_sel_hi:[1,0]
	v_pk_mul_f32 v[160:161], v[160:161], v[88:89] op_sel_hi:[1,0]
	v_cvt_pk_bf16_f32 v54, v48, v49
	v_cvt_pk_bf16_f32 v55, v50, v51
	v_cvt_pk_bf16_f32 v88, v40, v41
	v_cvt_pk_bf16_f32 v89, v42, v43
	ds_write2_b64 v157, v[54:55], v[88:89] offset1:4
	v_cvt_pk_bf16_f32 v54, v44, v45
	v_cvt_pk_bf16_f32 v55, v46, v47
	v_cvt_pk_bf16_f32 v88, v36, v37
	v_cvt_pk_bf16_f32 v89, v38, v39
	ds_write2_b64 v157, v[54:55], v[88:89] offset0:8 offset1:12
	s_waitcnt vmcnt(9)
	v_lshlrev_b32_e32 v54, 16, v52
	v_and_b32_e32 v55, 0xffff0000, v52
	v_mul_f32_e32 v2, 0xbfb8aa3b, v54
	v_exp_f32_e32 v2, v2
	v_mul_f32_e32 v52, 0xbfb8aa3b, v55
	v_exp_f32_e32 v52, v52
	s_waitcnt lgkmcnt(5)
	v_mfma_f32_16x16x32_bf16 v[164:167], v[176:179], v[180:183], v[164:167]
	ds_read_b64 v[88:89], v132
	v_add_f32_e32 v2, 1.0, v2
	v_rcp_f32_e32 v156, v2
	v_add_f32_e32 v2, 1.0, v52
	s_waitcnt lgkmcnt(4)
	v_mfma_f32_16x16x32_bf16 v[158:161], v[176:179], v[192:195], v[160:163]
	v_rcp_f32_e32 v157, v2
	v_lshlrev_b32_e32 v52, 16, v53
	v_and_b32_e32 v53, 0xffff0000, v53
	v_mfma_f32_16x16x32_bf16 v[162:165], v[184:187], v[188:191], v[164:167]
	v_mul_f32_e64 v54, v156, v54
	v_mul_f32_e64 v55, v157, v55
	v_mul_f32_e32 v2, 0xbfb8aa3b, v52
	v_exp_f32_e32 v2, v2
	s_waitcnt lgkmcnt(0)
	v_lshlrev_b32_e32 v166, 16, v88
	v_and_b32_e32 v167, 0xffff0000, v88
	s_nop 0
	v_pk_fma_f32 v[162:163], v[0:1], v[166:167], v[162:163]
	v_add_f32_e32 v2, 1.0, v2
	v_pk_mul_f32 v[156:157], v[54:55], v[162:163]
	v_mul_f32_e32 v54, 0xbfb8aa3b, v53
	v_exp_f32_e32 v88, v54
	v_rcp_f32_e32 v162, v2
	v_pk_mul_f32 v[54:55], v[156:157], v[156:157]
	v_cvt_pk_bf16_f32 v156, v156, v157
	v_add_f32_e32 v2, 1.0, v88
	v_rcp_f32_e32 v163, v2
	v_lshlrev_b32_e32 v88, 16, v89
	v_and_b32_e32 v89, 0xffff0000, v89
	v_pk_fma_f32 v[88:89], v[0:1], v[88:89], v[164:165]
	v_pk_mul_f32 v[52:53], v[162:163], v[52:53]
	v_add_f32_e32 v2, v54, v55
	v_pk_mul_f32 v[162:163], v[52:53], v[88:89]
	v_lshl_add_u64 v[92:93], v[86:87], 0, v[92:93]
	v_pk_mul_f32 v[52:53], v[162:163], v[162:163]
	v_cvt_pk_bf16_f32 v157, v162, v163
	v_add_f32_e32 v2, v52, v2
	v_add_f32_e32 v2, v53, v2
	ds_bpermute_b32 v88, v153, v2
	v_mfma_f32_16x16x32_bf16 v[52:55], v[184:187], v[202:205], v[158:161]
	global_store_dwordx2 v[92:93], v[156:157], off
	s_waitcnt lgkmcnt(0)
	v_add_f32_e32 v2, v2, v88
	ds_bpermute_b32 v88, v154, v2
	s_and_saveexec_b64 s[0:1], s[58:59]
	s_cbranch_execz .LBB0_375
	s_waitcnt lgkmcnt(0)
	v_add_f32_e32 v2, v2, v88
	ds_write_b32 v114, v2
